# QKV q tiles (K=256 gemm_tile_glds, both layers): stage-1 LDS-DMA issue hoisted behind stage-0 issue (address temps renamed to free VGPRs); first wait vmcnt(8)
# speedup vs baseline: 1.0021x; 1.0005x over previous
.LBB0_612:
	s_mul_hi_i32 s0, s83, 0x55555556
	s_lshr_b32 s1, s0, 31
	s_waitcnt vmcnt(0)
	v_mov_b32_e32 v46, v164
	s_add_i32 s0, s0, s1
	s_lshl_b32 s1, s0, 7
	v_bfe_u32 v4, v46, 3, 5
	v_xor_b32_e32 v5, v4, v46
	v_or_b32_e32 v6, s1, v4
	v_mov_b64_e32 v[0:1], s[16:17]
	v_lshlrev_b32_e32 v5, 4, v5
	v_mad_i64_i32 v[0:1], s[4:5], v6, s80, v[0:1]
	v_and_b32_e32 v64, 0x70, v5
	s_mulk_i32 s0, 0x180
	v_lshl_add_u64 v[38:39], v[0:1], 0, v[64:65]
	v_subrev_u32_e32 v0, s0, v4
	v_and_b32_e32 v3, 0xff, v46
	v_add_u32_e32 v0, s74, v0
	v_ashrrev_i32_e32 v1, 31, v0
	v_lshl_add_u32 v40, v3, 4, s23
	v_lshlrev_b64 v[0:1], 9, v[0:1]
	v_readfirstlane_b32 s70, v40
	v_add_u32_e32 v3, 0x1000, v40
	v_lshl_add_u64 v[0:1], s[30:31], 0, v[0:1]
	s_mov_b32 m0, s70
	v_readfirstlane_b32 s51, v3
	v_add_u32_e32 v3, 0x2000, v40
	v_lshl_add_u64 v[36:37], v[0:1], 0, v[64:65]
	global_load_lds_dwordx4 v[38:39], off
	v_lshl_add_u64 v[0:1], v[38:39], 0, s[36:37]
	s_mov_b32 m0, s51
	v_readfirstlane_b32 s49, v3
	v_add_u32_e32 v3, 0x3000, v40
	global_load_lds_dwordx4 v[0:1], off
	v_lshl_add_u64 v[0:1], v[38:39], 0, s[38:39]
	s_mov_b32 m0, s49
	v_readfirstlane_b32 s48, v3
	global_load_lds_dwordx4 v[0:1], off
	v_lshl_add_u64 v[0:1], v[38:39], 0, s[52:53]
	s_mov_b32 m0, s48
	v_add_u32_e32 v3, 0x5000, v40
	global_load_lds_dwordx4 v[0:1], off
	v_add_u32_e32 v0, 0x4000, v40
	v_readfirstlane_b32 s34, v3
	v_readfirstlane_b32 s43, v0
	s_mov_b32 m0, s43
	v_lshl_add_u64 v[0:1], v[36:37], 0, s[54:55]
	global_load_lds_dwordx4 v[36:37], off
	s_mov_b32 m0, s34
	s_mov_b64 s[4:5], 0x8000
	v_add_u32_e32 v3, 0x6000, v40
	global_load_lds_dwordx4 v[0:1], off
	v_lshl_add_u64 v[0:1], v[36:37], 0, s[4:5]
	v_readfirstlane_b32 s5, v3
	v_add_u32_e32 v3, 0x7000, v40
	s_mov_b32 m0, s5
	s_mov_b64 s[40:41], 0xc000
	v_readfirstlane_b32 s4, v3
	v_lshrrev_b32_e32 v2, 4, v46
	v_and_b32_e32 v47, 15, v46
	global_load_lds_dwordx4 v[0:1], off
	v_lshl_add_u64 v[0:1], v[36:37], 0, s[40:41]
	s_mov_b32 m0, s4
	v_and_b32_e32 v41, 7, v46
	v_bfe_u32 v44, v46, 6, 1
	global_load_lds_dwordx4 v[0:1], off
	s_mov_b64 s[84:85], 0x8080
	s_mov_b64 s[86:87], 0xc080
	v_lshl_add_u64 v[62:63], v[36:37], 0, s[86:87]
	v_add_u32_e32 v233, 0xc000, v40
	v_lshl_add_u64 v[234:235], v[36:37], 0, s[58:59]
	v_readfirstlane_b32 s50, v233
	v_add_u32_e32 v233, 0xd000, v40
	v_add_u32_e32 v202, 0x8000, v40
	v_lshl_add_u64 v[200:201], v[38:39], 0, s[58:59]
	v_readfirstlane_b32 s2, v202
	s_mov_b32 m0, s2
	s_nop 0
	global_load_lds_dwordx4 v[200:201], off
	v_add_u32_e32 v200, 0x9000, v40
	s_nop 0
	v_readfirstlane_b32 s41, v200
	s_mov_b32 m0, s41
	v_readfirstlane_b32 s71, v233
	v_add_u32_e32 v233, 0xe000, v40
	v_add_u32_e32 v218, 0xa000, v40
	s_nop 0
	v_readfirstlane_b32 s40, v218
	v_lshl_add_u64 v[216:217], v[38:39], 0, s[62:63]
	v_lshl_add_u64 v[204:205], v[38:39], 0, s[64:65]
	v_add_u32_e32 v220, 0xb000, v40
	global_load_lds_dwordx4 v[204:205], off
	s_mov_b32 m0, s40
	v_readfirstlane_b32 s42, v220
	global_load_lds_dwordx4 v[216:217], off
	s_mov_b32 m0, s42
	v_lshl_add_u64 v[224:225], v[38:39], 0, s[60:61]
	global_load_lds_dwordx4 v[224:225], off
	s_mov_b32 m0, s50
	s_nop 0
	global_load_lds_dwordx4 v[234:235], off
	v_lshl_add_u64 v[234:235], v[36:37], 0, s[56:57]
	s_mov_b32 m0, s71
	v_add_u32_e32 v40, 0xf000, v40
	global_load_lds_dwordx4 v[234:235], off
	v_lshl_add_u64 v[234:235], v[36:37], 0, s[84:85]
	v_readfirstlane_b32 s84, v233
	s_mov_b32 m0, s84
	v_readfirstlane_b32 s85, v40
	global_load_lds_dwordx4 v[234:235], off
	s_mov_b32 m0, s85
	s_nop 0
	global_load_lds_dwordx4 v[62:63], off
	v_bitop3_b32 v0, v2, v41, 3 bitop3:0x6c
	v_lshlrev_b32_e32 v5, 7, v47
	v_bfe_u32 v45, v46, 7, 1
	v_lshl_add_u32 v4, v0, 4, s23
	v_lshl_or_b32 v42, v44, 13, v5
	v_add_u32_e32 v50, v4, v42
	v_lshl_or_b32 v43, v45, 13, v5
	s_waitcnt vmcnt(8)
	s_waitcnt vmcnt(8) lgkmcnt(0)
	s_barrier
	ds_read_b128 v[0:3], v50 offset:16384
	v_add_u32_e32 v49, v4, v43
	ds_read_b128 v[4:7], v50 offset:18432
	ds_read_b128 v[8:11], v49
	ds_read_b128 v[12:15], v49 offset:2048
	ds_read_b128 v[20:23], v50 offset:20480
	ds_read_b128 v[28:31], v50 offset:22528
	s_waitcnt lgkmcnt(3)
	v_mfma_f32_16x16x32_bf16 v[16:19], v[0:3], v[8:11], 0
	v_bfe_u32 v48, v46, 4, 2
	v_mfma_f32_16x16x32_bf16 v[24:27], v[4:7], v[8:11], 0
	s_mov_b64 s[86:87], 0x26d00
	v_and_b32_e32 v46, 0x80, v46
	s_waitcnt lgkmcnt(1)
	v_mfma_f32_16x16x32_bf16 v[32:35], v[20:23], v[8:11], 0
	s_waitcnt lgkmcnt(0)
	v_mfma_f32_16x16x32_bf16 v[54:57], v[28:31], v[8:11], 0
	v_mfma_f32_16x16x32_bf16 v[58:61], v[0:3], v[12:15], 0
	v_mfma_f32_16x16x32_bf16 v[68:71], v[4:7], v[12:15], 0
	v_mfma_f32_16x16x32_bf16 v[72:75], v[20:23], v[12:15], 0
	v_mfma_f32_16x16x32_bf16 v[76:79], v[28:31], v[12:15], 0
	ds_read_b128 v[8:11], v49 offset:4096
	ds_read_b128 v[12:15], v49 offset:6144
	s_waitcnt lgkmcnt(1)
	v_mfma_f32_16x16x32_bf16 v[80:83], v[0:3], v[8:11], 0
	s_waitcnt lgkmcnt(0)
	v_mfma_f32_16x16x32_bf16 v[96:99], v[0:3], v[12:15], 0
	v_bitop3_b32 v0, v48, v41, 4 bitop3:0x36
	v_lshl_add_u32 v0, v0, 4, s23
	v_add_u32_e32 v52, v0, v42
	ds_read_b128 v[104:107], v52 offset:16384
	v_mfma_f32_16x16x32_bf16 v[84:87], v[4:7], v[8:11], 0
	v_add_u32_e32 v51, v0, v43
	v_mfma_f32_16x16x32_bf16 v[88:91], v[20:23], v[8:11], 0
	v_mfma_f32_16x16x32_bf16 v[92:95], v[28:31], v[8:11], 0
	v_mfma_f32_16x16x32_bf16 v[108:111], v[20:23], v[12:15], 0
	ds_read_b128 v[20:23], v51
	ds_read_b128 v[112:115], v52 offset:18432
	ds_read_b128 v[116:119], v51 offset:2048
	ds_read_b128 v[120:123], v52 offset:20480
	s_waitcnt lgkmcnt(0)
	v_mfma_f32_16x16x32_bf16 v[0:3], v[104:107], v[20:23], v[16:19]
	s_nop 1
	ds_read_b128 v[16:19], v52 offset:22528
	v_mfma_f32_16x16x32_bf16 v[8:11], v[112:115], v[20:23], v[24:27]
	v_mfma_f32_16x16x32_bf16 v[100:103], v[4:7], v[12:15], 0
	v_mfma_f32_16x16x32_bf16 v[4:7], v[28:31], v[12:15], 0
	v_mfma_f32_16x16x32_bf16 v[12:15], v[120:123], v[20:23], v[32:35]
	s_nop 0
	s_waitcnt lgkmcnt(0)
	v_mfma_f32_16x16x32_bf16 v[20:23], v[16:19], v[20:23], v[54:57]
	s_nop 0
	ds_read_b128 v[54:57], v51 offset:4096
	v_mfma_f32_16x16x32_bf16 v[24:27], v[104:107], v[116:119], v[58:61]
	s_mov_b32 m0, s70
	v_mfma_f32_16x16x32_bf16 v[28:31], v[112:115], v[116:119], v[68:71]
	v_lshl_add_u64 v[62:63], v[38:39], 0, s[86:87]
	s_mov_b64 s[86:87], 0x4d900
	v_mfma_f32_16x16x32_bf16 v[32:35], v[120:123], v[116:119], v[72:75]
	ds_read_b128 v[68:71], v51 offset:6144
	s_waitcnt vmcnt(0)
	s_waitcnt vmcnt(0) lgkmcnt(0)
	v_mfma_f32_16x16x32_bf16 v[58:61], v[16:19], v[116:119], v[76:79]
	s_barrier
	v_mfma_f32_16x16x32_bf16 v[72:75], v[104:107], v[54:57], v[80:83]
	v_mfma_f32_16x16x32_bf16 v[76:79], v[112:115], v[54:57], v[84:87]
	v_mfma_f32_16x16x32_bf16 v[80:83], v[120:123], v[54:57], v[88:91]
	v_mfma_f32_16x16x32_bf16 v[54:57], v[16:19], v[54:57], v[92:95]
	s_nop 2
	ds_read_b128 v[92:95], v50 offset:49152
	v_mfma_f32_16x16x32_bf16 v[84:87], v[104:107], v[68:71], v[96:99]
	v_mfma_f32_16x16x32_bf16 v[40:43], v[112:115], v[68:71], v[100:103]
	v_mfma_f32_16x16x32_bf16 v[88:91], v[120:123], v[68:71], v[108:111]
	v_mfma_f32_16x16x32_bf16 v[4:7], v[16:19], v[68:71], v[4:7]
	ds_read_b128 v[16:19], v50 offset:51200
	ds_read_b128 v[68:71], v49 offset:32768
	ds_read_b128 v[96:99], v49 offset:34816
	ds_read_b128 v[104:107], v50 offset:55296
	s_waitcnt lgkmcnt(2)
	v_mfma_f32_16x16x32_bf16 v[100:103], v[92:95], v[68:71], v[0:3]
	s_nop 2
	ds_read_b128 v[0:3], v50 offset:53248
	v_mfma_f32_16x16x32_bf16 v[8:11], v[16:19], v[68:71], v[8:11]
	s_waitcnt lgkmcnt(0)
	v_mfma_f32_16x16x32_bf16 v[12:15], v[0:3], v[68:71], v[12:15]
	v_mfma_f32_16x16x32_bf16 v[20:23], v[104:107], v[68:71], v[20:23]
	v_mfma_f32_16x16x32_bf16 v[24:27], v[92:95], v[96:99], v[24:27]
	v_mfma_f32_16x16x32_bf16 v[28:31], v[16:19], v[96:99], v[28:31]
	v_mfma_f32_16x16x32_bf16 v[68:71], v[0:3], v[96:99], v[32:35]
	v_mfma_f32_16x16x32_bf16 v[58:61], v[104:107], v[96:99], v[58:61]
	s_nop 1
	ds_read_b128 v[32:35], v49 offset:36864
	ds_read_b128 v[96:99], v49 offset:38912
	s_waitcnt lgkmcnt(1)
	v_mfma_f32_16x16x32_bf16 v[72:75], v[92:95], v[32:35], v[72:75]
	v_mfma_f32_16x16x32_bf16 v[76:79], v[16:19], v[32:35], v[76:79]
	v_mfma_f32_16x16x32_bf16 v[80:83], v[0:3], v[32:35], v[80:83]
	v_mfma_f32_16x16x32_bf16 v[54:57], v[104:107], v[32:35], v[54:57]
	v_lshl_add_u64 v[32:33], v[38:39], 0, s[66:67]
	s_waitcnt lgkmcnt(0)
	v_mfma_f32_16x16x32_bf16 v[84:87], v[92:95], v[96:99], v[84:87]
	ds_read_b128 v[92:95], v52 offset:49152
	v_mfma_f32_16x16x32_bf16 v[40:43], v[16:19], v[96:99], v[40:43]
	v_mfma_f32_16x16x32_bf16 v[88:91], v[0:3], v[96:99], v[88:91]
	v_mfma_f32_16x16x32_bf16 v[0:3], v[104:107], v[96:99], v[4:7]
	ds_read_b128 v[16:19], v51 offset:32768
	ds_read_b128 v[96:99], v52 offset:51200
	ds_read_b128 v[104:107], v51 offset:34816
	ds_read_b128 v[108:111], v52 offset:53248
	global_load_lds_dwordx4 v[32:33], off
	ds_read_b128 v[32:35], v52 offset:55296
	s_mov_b32 m0, s51
	s_waitcnt lgkmcnt(0)
	v_mfma_f32_16x16x32_bf16 v[4:7], v[92:95], v[16:19], v[100:103]
	global_load_lds_dwordx4 v[62:63], off
	v_lshl_add_u64 v[62:63], v[38:39], 0, s[86:87]
	s_mov_b32 m0, s49
	s_mov_b64 s[86:87], 0x74500
	global_load_lds_dwordx4 v[62:63], off
	v_lshl_add_u64 v[62:63], v[38:39], 0, s[86:87]
	s_mov_b32 m0, s48
	v_mfma_f32_16x16x32_bf16 v[8:11], v[96:99], v[16:19], v[8:11]
	global_load_lds_dwordx4 v[62:63], off
	v_lshl_add_u64 v[62:63], v[36:37], 0, s[66:67]
	v_mfma_f32_16x16x32_bf16 v[12:15], v[108:111], v[16:19], v[12:15]
	s_mov_b32 m0, s43
	ds_read_b128 v[100:103], v51 offset:38912
	s_mov_b64 s[48:49], 0x4100
	v_mfma_f32_16x16x32_bf16 v[16:19], v[32:35], v[16:19], v[20:23]
	global_load_lds_dwordx4 v[62:63], off
	v_lshl_add_u64 v[62:63], v[36:37], 0, s[48:49]
	v_mfma_f32_16x16x32_bf16 v[20:23], v[92:95], v[104:107], v[24:27]
	s_mov_b32 m0, s34
	s_mov_b64 s[48:49], 0x8100
	global_load_lds_dwordx4 v[62:63], off
	v_mfma_f32_16x16x32_bf16 v[24:27], v[96:99], v[104:107], v[28:31]
	v_lshl_add_u64 v[62:63], v[36:37], 0, s[48:49]
	s_mov_b32 m0, s5
	s_mov_b64 s[48:49], 0xc100
	v_mfma_f32_16x16x32_bf16 v[28:31], v[108:111], v[104:107], v[68:71]
	global_load_lds_dwordx4 v[62:63], off
	v_lshl_add_u64 v[62:63], v[36:37], 0, s[48:49]
	s_nop 0
	ds_read_b128 v[68:71], v51 offset:36864
	s_mov_b32 m0, s4
	v_mfma_f32_16x16x32_bf16 v[58:61], v[32:35], v[104:107], v[58:61]
	global_load_lds_dwordx4 v[62:63], off
	s_waitcnt vmcnt(0)
	s_waitcnt lgkmcnt(0)
	v_mfma_f32_16x16x32_bf16 v[72:75], v[92:95], v[68:71], v[72:75]
	s_waitcnt vmcnt(0)
	s_barrier
	v_mfma_f32_16x16x32_bf16 v[76:79], v[96:99], v[68:71], v[76:79]
	v_lshl_add_u64 v[62:63], v[38:39], 0, s[68:69]
	s_mov_b32 m0, s2
	s_mov_b64 s[4:5], 0x26d80
	v_mfma_f32_16x16x32_bf16 v[80:83], v[108:111], v[68:71], v[80:83]
	v_mfma_f32_16x16x32_bf16 v[54:57], v[32:35], v[68:71], v[54:57]
	v_mfma_f32_16x16x32_bf16 v[68:71], v[92:95], v[100:103], v[84:87]
	v_mfma_f32_16x16x32_bf16 v[40:43], v[96:99], v[100:103], v[40:43]
	v_mfma_f32_16x16x32_bf16 v[84:87], v[108:111], v[100:103], v[88:91]
	s_nop 2
	ds_read_b128 v[88:91], v50 offset:16384
	v_mfma_f32_16x16x32_bf16 v[0:3], v[32:35], v[100:103], v[0:3]
	ds_read_b128 v[32:35], v50 offset:18432
	ds_read_b128 v[92:95], v49
	ds_read_b128 v[96:99], v49 offset:2048
	ds_read_b128 v[100:103], v50 offset:20480
	ds_read_b128 v[104:107], v50 offset:22528
	s_waitcnt lgkmcnt(3)
	v_mfma_f32_16x16x32_bf16 v[4:7], v[88:91], v[92:95], v[4:7]
	v_mfma_f32_16x16x32_bf16 v[8:11], v[32:35], v[92:95], v[8:11]
	s_waitcnt lgkmcnt(1)
	v_mfma_f32_16x16x32_bf16 v[12:15], v[100:103], v[92:95], v[12:15]
	s_waitcnt lgkmcnt(0)
	v_mfma_f32_16x16x32_bf16 v[16:19], v[104:107], v[92:95], v[16:19]
	v_mfma_f32_16x16x32_bf16 v[20:23], v[88:91], v[96:99], v[20:23]
	v_mfma_f32_16x16x32_bf16 v[24:27], v[32:35], v[96:99], v[24:27]
	v_mfma_f32_16x16x32_bf16 v[28:31], v[100:103], v[96:99], v[28:31]
	v_mfma_f32_16x16x32_bf16 v[58:61], v[104:107], v[96:99], v[58:61]
	ds_read_b128 v[92:95], v49 offset:4096
	ds_read_b128 v[96:99], v49 offset:6144
	s_waitcnt lgkmcnt(1)
	v_mfma_f32_16x16x32_bf16 v[72:75], v[88:91], v[92:95], v[72:75]
	v_mfma_f32_16x16x32_bf16 v[76:79], v[32:35], v[92:95], v[76:79]
	v_mfma_f32_16x16x32_bf16 v[80:83], v[100:103], v[92:95], v[80:83]
	v_mfma_f32_16x16x32_bf16 v[54:57], v[104:107], v[92:95], v[54:57]
	s_waitcnt lgkmcnt(0)
	v_mfma_f32_16x16x32_bf16 v[68:71], v[88:91], v[96:99], v[68:71]
	v_mfma_f32_16x16x32_bf16 v[88:91], v[32:35], v[96:99], v[40:43]
	ds_read_b128 v[32:35], v52 offset:16384
	s_nop 1
	ds_read_b128 v[40:43], v51
	ds_read_b128 v[92:95], v52 offset:18432
	v_mfma_f32_16x16x32_bf16 v[84:87], v[100:103], v[96:99], v[84:87]
	v_mfma_f32_16x16x32_bf16 v[0:3], v[104:107], v[96:99], v[0:3]
	ds_read_b128 v[96:99], v51 offset:2048
	ds_read_b128 v[100:103], v52 offset:20480
	ds_read_b128 v[104:107], v52 offset:22528
	global_load_lds_dwordx4 v[62:63], off
	v_lshl_add_u64 v[62:63], v[38:39], 0, s[4:5]
	s_mov_b32 m0, s41
	s_mov_b64 s[4:5], 0x4d980
	s_waitcnt lgkmcnt(0)
	v_mfma_f32_16x16x32_bf16 v[4:7], v[32:35], v[40:43], v[4:7]
	global_load_lds_dwordx4 v[62:63], off
	s_mov_b32 m0, s40
	v_mfma_f32_16x16x32_bf16 v[8:11], v[92:95], v[40:43], v[8:11]
	v_mfma_f32_16x16x32_bf16 v[12:15], v[100:103], v[40:43], v[12:15]
	v_mfma_f32_16x16x32_bf16 v[16:19], v[104:107], v[40:43], v[16:19]
	v_lshl_add_u64 v[40:41], v[38:39], 0, s[4:5]
	s_mov_b64 s[4:5], 0x74580
	global_load_lds_dwordx4 v[40:41], off
	v_mfma_f32_16x16x32_bf16 v[108:111], v[92:95], v[96:99], v[24:27]
	s_mov_b32 m0, s42
	s_nop 1
	v_lshl_add_u64 v[24:25], v[38:39], 0, s[4:5]
	global_load_lds_dwordx4 v[24:25], off
	ds_read_b128 v[24:27], v51 offset:4096
	v_mfma_f32_16x16x32_bf16 v[20:23], v[32:35], v[96:99], v[20:23]
	s_mov_b32 m0, s50
	s_mov_b64 s[4:5], 0x4180
	v_mfma_f32_16x16x32_bf16 v[112:115], v[100:103], v[96:99], v[28:31]
	s_nop 2
	v_lshl_add_u64 v[28:29], v[36:37], 0, s[68:69]
	v_mfma_f32_16x16x32_bf16 v[58:61], v[104:107], v[96:99], v[58:61]
	ds_read_b128 v[96:99], v51 offset:6144
	global_load_lds_dwordx4 v[28:29], off
	v_lshl_add_u64 v[28:29], v[36:37], 0, s[4:5]
	s_mov_b32 m0, s71
	s_mov_b64 s[4:5], 0x8180
	global_load_lds_dwordx4 v[28:29], off
	v_lshl_add_u64 v[28:29], v[36:37], 0, s[4:5]
	s_mov_b32 m0, s84
	s_mov_b64 s[4:5], 0xc180
	s_waitcnt lgkmcnt(0)
	v_mfma_f32_16x16x32_bf16 v[72:75], v[32:35], v[24:27], v[72:75]
	global_load_lds_dwordx4 v[28:29], off
	s_mov_b32 m0, s85
	v_mfma_f32_16x16x32_bf16 v[76:79], v[92:95], v[24:27], v[76:79]
	v_mfma_f32_16x16x32_bf16 v[80:83], v[100:103], v[24:27], v[80:83]
	v_mfma_f32_16x16x32_bf16 v[40:43], v[104:107], v[24:27], v[54:57]
	v_lshl_add_u64 v[24:25], v[36:37], 0, s[4:5]
	global_load_lds_dwordx4 v[24:25], off
	v_mfma_f32_16x16x32_bf16 v[32:35], v[32:35], v[96:99], v[68:71]
	s_waitcnt vmcnt(0)
	s_waitcnt vmcnt(0) lgkmcnt(0)
	s_barrier
	v_mfma_f32_16x16x32_bf16 v[28:31], v[92:95], v[96:99], v[88:91]
	ds_read_b128 v[54:57], v50 offset:49152
	ds_read_b128 v[120:123], v49 offset:34816
	v_mfma_f32_16x16x32_bf16 v[24:27], v[100:103], v[96:99], v[84:87]
	ds_read_b128 v[88:91], v50 offset:51200
	v_mfma_f32_16x16x32_bf16 v[68:71], v[104:107], v[96:99], v[0:3]
	ds_read_b128 v[96:99], v50 offset:53248
	ds_read_b128 v[104:107], v50 offset:55296
	s_nop 0
	ds_read_b128 v[0:3], v49 offset:32768
	s_waitcnt lgkmcnt(0)
	v_mfma_f32_16x16x32_bf16 v[84:87], v[54:57], v[0:3], v[4:7]
	v_mfma_f32_16x16x32_bf16 v[92:95], v[88:91], v[0:3], v[8:11]
	v_mfma_f32_16x16x32_bf16 v[100:103], v[96:99], v[0:3], v[12:15]
	v_mfma_f32_16x16x32_bf16 v[116:119], v[104:107], v[0:3], v[16:19]
	ds_read_b128 v[0:3], v52 offset:55296
	ds_read_b128 v[8:11], v52 offset:53248
	ds_read_b128 v[12:15], v52 offset:51200
	ds_read_b128 v[16:19], v52 offset:49152
	v_mfma_f32_16x16x32_bf16 v[124:127], v[54:57], v[120:123], v[20:23]
	ds_read_b128 v[4:7], v51 offset:38912
	s_nop 1
	ds_read_b128 v[20:23], v51 offset:36864
	ds_read_b128 v[36:39], v51 offset:34816
	ds_read_b128 v[50:53], v51 offset:32768
	ds_read_b128 v[128:131], v49 offset:38912
	ds_read_b128 v[132:135], v49 offset:36864
	v_or_b32_e32 v49, s1, v47
	v_lshl_or_b32 v46, v49, 1, v46
	v_ashrrev_i32_e32 v47, 31, v46
	v_lshl_add_u64 v[46:47], v[46:47], 2, s[8:9]
	s_waitcnt vmcnt(0)
	s_waitcnt lgkmcnt(0)
	s_barrier
	global_load_dword v62, v[46:47], off
	global_load_dword v64, v[46:47], off offset:128
	v_mfma_f32_16x16x32_bf16 v[108:111], v[88:91], v[120:123], v[108:111]
	v_mfma_f32_16x16x32_bf16 v[112:115], v[96:99], v[120:123], v[112:115]
	v_mfma_f32_16x16x32_bf16 v[58:61], v[104:107], v[120:123], v[58:61]
	v_mfma_f32_16x16x32_bf16 v[120:123], v[104:107], v[132:135], v[40:43]
	global_load_dword v66, v[46:47], off offset:256
	s_nop 1
	global_load_dword v40, v[46:47], off offset:384
	v_lshlrev_b32_e32 v42, 2, v48
	v_lshl_or_b32 v42, v44, 6, v42
	v_subrev_u32_e32 v42, s0, v42
	v_lshl_or_b32 v41, v45, 6, v49
	v_add_u32_e32 v46, s74, v42
	v_mfma_f32_16x16x32_bf16 v[42:45], v[16:19], v[50:53], v[84:87]
	v_ashrrev_i32_e32 v47, 31, v46
	v_mfma_f32_16x16x32_bf16 v[72:75], v[54:57], v[132:135], v[72:75]
	s_nop 0
	v_lshlrev_b64 v[84:85], 1, v[46:47]
	s_waitcnt vmcnt(3)
	s_nop 2
	v_pk_mul_f32 v[42:43], v[42:43], v[62:63] op_sel_hi:[1,0]
	v_mfma_f32_16x16x32_bf16 v[32:35], v[54:57], v[128:131], v[32:35]
	v_cvt_pk_bf16_f32 v54, v42, v43
	v_pk_mul_f32 v[42:43], v[44:45], v[62:63] op_sel_hi:[1,0]
	s_nop 0
	v_cvt_pk_bf16_f32 v55, v42, v43
	v_mfma_f32_16x16x32_bf16 v[42:45], v[12:15], v[50:53], v[92:95]
	v_mfma_f32_16x16x32_bf16 v[76:79], v[88:91], v[132:135], v[76:79]
	v_mfma_f32_16x16x32_bf16 v[28:31], v[88:91], v[128:131], v[28:31]
	v_mov_b64_e32 v[88:89], s[10:11]
	v_mad_i64_i32 v[48:49], s[0:1], v41, s77, v[88:89]
	v_lshl_add_u64 v[56:57], v[48:49], 0, v[84:85]
	s_nop 2
	v_pk_mul_f32 v[42:43], v[42:43], v[62:63] op_sel_hi:[1,0]
	global_store_dwordx2 v[56:57], v[54:55], off
	v_cvt_pk_bf16_f32 v54, v42, v43
	v_pk_mul_f32 v[42:43], v[44:45], v[62:63] op_sel_hi:[1,0]
	v_mfma_f32_16x16x32_bf16 v[80:83], v[96:99], v[132:135], v[80:83]
	v_cvt_pk_bf16_f32 v55, v42, v43
	global_store_dwordx2 v[56:57], v[54:55], off offset:32
	v_mfma_f32_16x16x32_bf16 v[42:45], v[8:11], v[50:53], v[100:103]
	v_mfma_f32_16x16x32_bf16 v[50:53], v[0:3], v[50:53], v[116:119]
	v_mfma_f32_16x16x32_bf16 v[24:27], v[96:99], v[128:131], v[24:27]
	s_nop 5
	v_mul_f32_e64 v42, v42, v62
	v_mul_f32_e64 v43, v43, v62
	v_pk_mul_f32 v[44:45], v[44:45], v[62:63] op_sel_hi:[1,0]
	v_cvt_pk_bf16_f32 v42, v42, v43
	v_cvt_pk_bf16_f32 v43, v44, v45
	global_store_dwordx2 v[56:57], v[42:43], off offset:64
	v_mfma_f32_16x16x32_bf16 v[42:45], v[16:19], v[36:39], v[124:127]
	v_mul_f32_e64 v50, v50, v62
	v_mul_f32_e64 v51, v51, v62
	v_pk_mul_f32 v[62:63], v[52:53], v[62:63] op_sel_hi:[1,0]
	v_cvt_pk_bf16_f32 v54, v50, v51
	v_mfma_f32_16x16x32_bf16 v[50:53], v[12:15], v[36:39], v[108:111]
	v_cvt_pk_bf16_f32 v55, v62, v63
	v_or_b32_e32 v62, 16, v41
	s_waitcnt vmcnt(5)
	v_pk_mul_f32 v[42:43], v[42:43], v[64:65] op_sel_hi:[1,0]
	global_store_dwordx2 v[56:57], v[54:55], off offset:96
	v_mfma_f32_16x16x32_bf16 v[54:57], v[8:11], v[36:39], v[112:115]
	v_mad_i64_i32 v[62:63], s[0:1], v62, s77, v[88:89]
	v_lshl_add_u64 v[62:63], v[62:63], 0, v[84:85]
	v_mfma_f32_16x16x32_bf16 v[36:39], v[0:3], v[36:39], v[58:61]
	v_mul_f32_e64 v50, v50, v64
	v_mul_f32_e64 v51, v51, v64
	s_nop 2
	v_pk_mul_f32 v[54:55], v[54:55], v[64:65] op_sel_hi:[1,0]
	v_pk_mul_f32 v[56:57], v[56:57], v[64:65] op_sel_hi:[1,0]
	v_cvt_pk_bf16_f32 v58, v42, v43
	v_pk_mul_f32 v[42:43], v[44:45], v[64:65] op_sel_hi:[1,0]
	v_mfma_f32_16x16x32_bf16 v[46:49], v[104:107], v[128:131], v[68:71]
	v_cvt_pk_bf16_f32 v59, v42, v43
	global_store_dwordx2 v[62:63], v[58:59], off
	v_cvt_pk_bf16_f32 v54, v54, v55
	v_mfma_f32_16x16x32_bf16 v[42:45], v[16:19], v[20:23], v[72:75]
	v_cvt_pk_bf16_f32 v68, v50, v51
	v_pk_mul_f32 v[50:51], v[52:53], v[64:65] op_sel_hi:[1,0]
	v_cvt_pk_bf16_f32 v55, v56, v57
	v_mfma_f32_16x16x32_bf16 v[58:61], v[12:15], v[20:23], v[76:79]
	v_cvt_pk_bf16_f32 v69, v50, v51
	global_store_dwordx2 v[62:63], v[68:69], off offset:32
	global_store_dwordx2 v[62:63], v[54:55], off offset:64
	v_mfma_f32_16x16x32_bf16 v[50:53], v[8:11], v[20:23], v[80:83]
	v_mfma_f32_16x16x32_bf16 v[12:15], v[12:15], v[4:7], v[28:31]
	s_nop 2
	v_or_b32_e32 v28, 32, v41
	v_mfma_f32_16x16x32_bf16 v[20:23], v[0:3], v[20:23], v[120:123]
	v_mfma_f32_16x16x32_bf16 v[16:19], v[16:19], v[4:7], v[32:35]
	v_mfma_f32_16x16x32_bf16 v[8:11], v[8:11], v[4:7], v[24:27]
	s_nop 1
	v_mul_f32_e64 v32, v36, v64
	v_mul_f32_e64 v33, v37, v64
	v_pk_mul_f32 v[34:35], v[38:39], v[64:65] op_sel_hi:[1,0]
	v_cvt_pk_bf16_f32 v32, v32, v33
	v_mad_i64_i32 v[24:25], s[0:1], v28, s77, v[88:89]
	s_waitcnt vmcnt(8)
	v_pk_mul_f32 v[26:27], v[42:43], v[66:67] op_sel_hi:[1,0]
	v_mfma_f32_16x16x32_bf16 v[0:3], v[0:3], v[4:7], v[46:49]
	v_mul_f32_e64 v4, v44, v66
	v_mul_f32_e64 v5, v45, v66
	v_cvt_pk_bf16_f32 v26, v26, v27
	v_cvt_pk_bf16_f32 v27, v4, v5
	v_lshl_add_u64 v[4:5], v[24:25], 0, v[84:85]
	v_pk_mul_f32 v[6:7], v[58:59], v[66:67] op_sel_hi:[1,0]
	v_pk_mul_f32 v[24:25], v[60:61], v[66:67] op_sel_hi:[1,0]
	v_cvt_pk_bf16_f32 v6, v6, v7
	v_cvt_pk_bf16_f32 v7, v24, v25
	global_store_dwordx2 v[4:5], v[6:7], off offset:32
	v_pk_mul_f32 v[6:7], v[50:51], v[66:67] op_sel_hi:[1,0]
	v_pk_mul_f32 v[24:25], v[52:53], v[66:67] op_sel_hi:[1,0]
	v_cvt_pk_bf16_f32 v6, v6, v7
	v_cvt_pk_bf16_f32 v7, v24, v25
	global_store_dwordx2 v[4:5], v[6:7], off offset:64
	v_pk_mul_f32 v[6:7], v[20:21], v[66:67] op_sel_hi:[1,0]
	v_pk_mul_f32 v[20:21], v[22:23], v[66:67] op_sel_hi:[1,0]
	v_cvt_pk_bf16_f32 v6, v6, v7
	v_cvt_pk_bf16_f32 v7, v20, v21
	global_store_dwordx2 v[4:5], v[26:27], off
	global_store_dwordx2 v[4:5], v[6:7], off offset:96
	v_or_b32_e32 v4, 48, v41
	v_mad_i64_i32 v[4:5], s[0:1], v4, s77, v[88:89]
	s_waitcnt vmcnt(11)
	v_pk_mul_f32 v[6:7], v[16:17], v[40:41] op_sel_hi:[1,0]
	v_pk_mul_f32 v[16:17], v[18:19], v[40:41] op_sel_hi:[1,0]
	v_cvt_pk_bf16_f32 v6, v6, v7
	v_cvt_pk_bf16_f32 v7, v16, v17
	v_lshl_add_u64 v[4:5], v[4:5], 0, v[84:85]
	global_store_dwordx2 v[4:5], v[6:7], off
	v_pk_mul_f32 v[6:7], v[12:13], v[40:41] op_sel_hi:[1,0]
	v_pk_mul_f32 v[12:13], v[14:15], v[40:41] op_sel_hi:[1,0]
	v_cvt_pk_bf16_f32 v6, v6, v7
	v_cvt_pk_bf16_f32 v7, v12, v13
	global_store_dwordx2 v[4:5], v[6:7], off offset:32
	v_pk_mul_f32 v[6:7], v[8:9], v[40:41] op_sel_hi:[1,0]
	v_pk_mul_f32 v[8:9], v[10:11], v[40:41] op_sel_hi:[1,0]
	v_pk_mul_f32 v[0:1], v[0:1], v[40:41] op_sel_hi:[1,0]
	v_pk_mul_f32 v[2:3], v[2:3], v[40:41] op_sel_hi:[1,0]
	v_cvt_pk_bf16_f32 v33, v34, v35
	v_cvt_pk_bf16_f32 v6, v6, v7
	v_cvt_pk_bf16_f32 v7, v8, v9
	v_cvt_pk_bf16_f32 v0, v0, v1
	v_cvt_pk_bf16_f32 v1, v2, v3
	global_store_dwordx2 v[62:63], v[32:33], off offset:96
	global_store_dwordx2 v[4:5], v[6:7], off offset:64
	global_store_dwordx2 v[4:5], v[0:1], off offset:96
	s_branch .LBB0_524

.LBB0_2076:
	s_mul_hi_i32 s2, s84, 0x55555556
	s_lshr_b32 s4, s2, 31
	v_mov_b32_e32 v48, v164
	s_add_i32 s2, s2, s4
	s_lshl_b32 s6, s2, 7
	v_bfe_u32 v4, v48, 3, 5
	v_xor_b32_e32 v5, v4, v48
	v_or_b32_e32 v6, s6, v4
	v_mov_b64_e32 v[0:1], s[18:19]
	v_lshlrev_b32_e32 v5, 4, v5
	v_mad_i64_i32 v[0:1], s[4:5], v6, s81, v[0:1]
	v_and_b32_e32 v64, 0x70, v5
	s_mulk_i32 s2, 0x180
	v_lshl_add_u64 v[40:41], v[0:1], 0, v[64:65]
	v_subrev_u32_e32 v0, s2, v4
	v_and_b32_e32 v3, 0xff, v48
	v_add_u32_e32 v0, s75, v0
	v_ashrrev_i32_e32 v1, 31, v0
	v_lshl_add_u32 v36, v3, 4, s23
	v_lshlrev_b64 v[0:1], 9, v[0:1]
	v_readfirstlane_b32 s56, v36
	v_add_u32_e32 v3, 0x1000, v36
	v_lshl_add_u64 v[0:1], s[34:35], 0, v[0:1]
	s_mov_b32 m0, s56
	v_readfirstlane_b32 s55, v3
	v_add_u32_e32 v3, 0x2000, v36
	v_lshl_add_u64 v[44:45], v[0:1], 0, v[64:65]
	global_load_lds_dwordx4 v[40:41], off
	v_lshl_add_u64 v[0:1], v[40:41], 0, s[38:39]
	s_mov_b32 m0, s55
	v_readfirstlane_b32 s53, v3
	v_add_u32_e32 v3, 0x3000, v36
	global_load_lds_dwordx4 v[0:1], off
	v_lshl_add_u64 v[0:1], v[40:41], 0, s[44:45]
	s_mov_b32 m0, s53
	v_readfirstlane_b32 s52, v3
	global_load_lds_dwordx4 v[0:1], off
	v_lshl_add_u64 v[0:1], v[40:41], 0, s[46:47]
	s_mov_b32 m0, s52
	v_add_u32_e32 v3, 0x5000, v36
	global_load_lds_dwordx4 v[0:1], off
	v_add_u32_e32 v0, 0x4000, v36
	v_readfirstlane_b32 s36, v3
	v_readfirstlane_b32 s43, v0
	s_mov_b32 m0, s43
	v_add_u32_e32 v3, 0x6000, v36
	global_load_lds_dwordx4 v[44:45], off
	v_lshl_add_u64 v[0:1], v[44:45], 0, s[48:49]
	s_mov_b32 m0, s36
	s_mov_b64 s[4:5], 0x8000
	v_readfirstlane_b32 s7, v3
	global_load_lds_dwordx4 v[0:1], off
	v_lshl_add_u64 v[0:1], v[44:45], 0, s[4:5]
	s_mov_b32 m0, s7
	s_mov_b64 s[4:5], 0xc000
	v_add_u32_e32 v3, 0x7000, v36
	global_load_lds_dwordx4 v[0:1], off
	v_lshl_add_u64 v[0:1], v[44:45], 0, s[4:5]
	v_readfirstlane_b32 s5, v3
	v_lshrrev_b32_e32 v2, 4, v48
	v_and_b32_e32 v49, 15, v48
	s_mov_b32 m0, s5
	v_and_b32_e32 v37, 7, v48
	v_bfe_u32 v46, v48, 6, 1
	global_load_lds_dwordx4 v[0:1], off
	s_mov_b64 s[86:87], 0x8080
	v_add_u32_e32 v229, 0xc000, v36
	v_lshl_add_u64 v[230:231], v[44:45], 0, s[58:59]
	v_readfirstlane_b32 s54, v229
	v_add_u32_e32 v229, 0xd000, v36
	v_add_u32_e32 v202, 0x8000, v36
	v_lshl_add_u64 v[200:201], v[40:41], 0, s[58:59]
	v_readfirstlane_b32 s4, v202
	s_mov_b32 m0, s4
	s_nop 0
	global_load_lds_dwordx4 v[200:201], off
	v_add_u32_e32 v200, 0x9000, v36
	s_nop 0
	v_readfirstlane_b32 s41, v200
	s_mov_b32 m0, s41
	v_readfirstlane_b32 s70, v229
	v_add_u32_e32 v229, 0xe000, v36
	v_add_u32_e32 v218, 0xa000, v36
	s_nop 0
	v_readfirstlane_b32 s40, v218
	v_lshl_add_u64 v[216:217], v[40:41], 0, s[62:63]
	v_readfirstlane_b32 s71, v229
	v_lshl_add_u64 v[204:205], v[40:41], 0, s[64:65]
	v_add_u32_e32 v220, 0xb000, v36
	global_load_lds_dwordx4 v[204:205], off
	s_mov_b32 m0, s40
	v_readfirstlane_b32 s42, v220
	global_load_lds_dwordx4 v[216:217], off
	s_mov_b32 m0, s42
	v_lshl_add_u64 v[224:225], v[40:41], 0, s[60:61]
	global_load_lds_dwordx4 v[224:225], off
	s_mov_b32 m0, s54
	s_nop 0
	global_load_lds_dwordx4 v[230:231], off
	v_lshl_add_u64 v[230:231], v[44:45], 0, s[50:51]
	s_mov_b32 m0, s70
	v_add_u32_e32 v36, 0xf000, v36
	global_load_lds_dwordx4 v[230:231], off
	v_lshl_add_u64 v[230:231], v[44:45], 0, s[86:87]
	s_mov_b32 m0, s71
	s_mov_b64 s[86:87], 0xc080
	v_readfirstlane_b32 s85, v36
	global_load_lds_dwordx4 v[230:231], off
	v_lshl_add_u64 v[42:43], v[44:45], 0, s[86:87]
	s_mov_b32 m0, s85
	s_nop 0
	global_load_lds_dwordx4 v[42:43], off
	v_bitop3_b32 v0, v2, v37, 3 bitop3:0x6c
	v_lshlrev_b32_e32 v5, 7, v49
	v_bfe_u32 v47, v48, 7, 1
	v_lshl_add_u32 v4, v0, 4, s23
	v_lshl_or_b32 v38, v46, 13, v5
	v_add_u32_e32 v52, v4, v38
	v_lshl_or_b32 v39, v47, 13, v5
	s_waitcnt vmcnt(8)
	s_waitcnt vmcnt(8) lgkmcnt(0)
	s_barrier
	ds_read_b128 v[0:3], v52 offset:16384
	v_add_u32_e32 v51, v4, v39
	ds_read_b128 v[4:7], v52 offset:18432
	ds_read_b128 v[8:11], v51
	ds_read_b128 v[12:15], v51 offset:2048
	ds_read_b128 v[20:23], v52 offset:20480
	ds_read_b128 v[28:31], v52 offset:22528
	s_waitcnt lgkmcnt(3)
	v_mfma_f32_16x16x32_bf16 v[16:19], v[0:3], v[8:11], 0
	v_bfe_u32 v50, v48, 4, 2
	v_mfma_f32_16x16x32_bf16 v[24:27], v[4:7], v[8:11], 0
	s_waitcnt lgkmcnt(1)
	v_mfma_f32_16x16x32_bf16 v[32:35], v[20:23], v[8:11], 0
	s_waitcnt lgkmcnt(0)
	v_mfma_f32_16x16x32_bf16 v[56:59], v[28:31], v[8:11], 0
	v_mfma_f32_16x16x32_bf16 v[60:63], v[0:3], v[12:15], 0
	v_mfma_f32_16x16x32_bf16 v[68:71], v[4:7], v[12:15], 0
	v_mfma_f32_16x16x32_bf16 v[72:75], v[20:23], v[12:15], 0
	v_mfma_f32_16x16x32_bf16 v[76:79], v[28:31], v[12:15], 0
	ds_read_b128 v[8:11], v51 offset:4096
	ds_read_b128 v[12:15], v51 offset:6144
	s_waitcnt lgkmcnt(1)
	v_mfma_f32_16x16x32_bf16 v[80:83], v[0:3], v[8:11], 0
	s_waitcnt lgkmcnt(0)
	v_mfma_f32_16x16x32_bf16 v[96:99], v[0:3], v[12:15], 0
	v_bitop3_b32 v0, v50, v37, 4 bitop3:0x36
	v_lshl_add_u32 v0, v0, 4, s23
	v_add_u32_e32 v54, v0, v38
	ds_read_b128 v[104:107], v54 offset:16384
	v_mfma_f32_16x16x32_bf16 v[84:87], v[4:7], v[8:11], 0
	v_add_u32_e32 v53, v0, v39
	v_mfma_f32_16x16x32_bf16 v[88:91], v[20:23], v[8:11], 0
	v_mfma_f32_16x16x32_bf16 v[92:95], v[28:31], v[8:11], 0
	v_mfma_f32_16x16x32_bf16 v[108:111], v[20:23], v[12:15], 0
	ds_read_b128 v[20:23], v53
	ds_read_b128 v[112:115], v54 offset:18432
	ds_read_b128 v[116:119], v53 offset:2048
	ds_read_b128 v[120:123], v54 offset:20480
	s_waitcnt lgkmcnt(0)
	v_mfma_f32_16x16x32_bf16 v[0:3], v[104:107], v[20:23], v[16:19]
	s_nop 1
	ds_read_b128 v[16:19], v54 offset:22528
	v_mfma_f32_16x16x32_bf16 v[8:11], v[112:115], v[20:23], v[24:27]
	v_mfma_f32_16x16x32_bf16 v[100:103], v[4:7], v[12:15], 0
	v_mfma_f32_16x16x32_bf16 v[4:7], v[28:31], v[12:15], 0
	v_mfma_f32_16x16x32_bf16 v[12:15], v[120:123], v[20:23], v[32:35]
	s_nop 0
	s_waitcnt lgkmcnt(0)
	v_mfma_f32_16x16x32_bf16 v[20:23], v[16:19], v[20:23], v[56:59]
	s_nop 0
	ds_read_b128 v[56:59], v53 offset:4096
	v_mfma_f32_16x16x32_bf16 v[24:27], v[104:107], v[116:119], v[60:63]
	s_mov_b32 m0, s56
	v_mfma_f32_16x16x32_bf16 v[28:31], v[112:115], v[116:119], v[68:71]
	s_mov_b64 s[86:87], 0x26d00
	v_lshl_add_u64 v[42:43], v[40:41], 0, s[86:87]
	s_mov_b64 s[86:87], 0x4d900
	v_mfma_f32_16x16x32_bf16 v[32:35], v[120:123], v[116:119], v[72:75]
	ds_read_b128 v[68:71], v53 offset:6144
	s_waitcnt vmcnt(0)
	s_waitcnt vmcnt(0) lgkmcnt(0)
	v_mfma_f32_16x16x32_bf16 v[60:63], v[16:19], v[116:119], v[76:79]
	s_barrier
	v_readlane_b32 s56, v255, 25
	v_mfma_f32_16x16x32_bf16 v[72:75], v[104:107], v[56:59], v[80:83]
	v_mfma_f32_16x16x32_bf16 v[76:79], v[112:115], v[56:59], v[84:87]
	v_mfma_f32_16x16x32_bf16 v[80:83], v[120:123], v[56:59], v[88:91]
	v_mfma_f32_16x16x32_bf16 v[56:59], v[16:19], v[56:59], v[92:95]
	s_nop 2
	ds_read_b128 v[92:95], v52 offset:49152
	v_mfma_f32_16x16x32_bf16 v[84:87], v[104:107], v[68:71], v[96:99]
	v_mfma_f32_16x16x32_bf16 v[36:39], v[112:115], v[68:71], v[100:103]
	v_mfma_f32_16x16x32_bf16 v[88:91], v[120:123], v[68:71], v[108:111]
	v_mfma_f32_16x16x32_bf16 v[4:7], v[16:19], v[68:71], v[4:7]
	ds_read_b128 v[16:19], v52 offset:51200
	ds_read_b128 v[68:71], v51 offset:32768
	ds_read_b128 v[96:99], v51 offset:34816
	ds_read_b128 v[104:107], v52 offset:55296
	s_waitcnt lgkmcnt(2)
	v_mfma_f32_16x16x32_bf16 v[100:103], v[92:95], v[68:71], v[0:3]
	s_nop 2
	ds_read_b128 v[0:3], v52 offset:53248
	v_mfma_f32_16x16x32_bf16 v[8:11], v[16:19], v[68:71], v[8:11]
	s_waitcnt lgkmcnt(0)
	v_mfma_f32_16x16x32_bf16 v[12:15], v[0:3], v[68:71], v[12:15]
	v_mfma_f32_16x16x32_bf16 v[20:23], v[104:107], v[68:71], v[20:23]
	v_mfma_f32_16x16x32_bf16 v[24:27], v[92:95], v[96:99], v[24:27]
	v_mfma_f32_16x16x32_bf16 v[28:31], v[16:19], v[96:99], v[28:31]
	v_mfma_f32_16x16x32_bf16 v[68:71], v[0:3], v[96:99], v[32:35]
	v_mfma_f32_16x16x32_bf16 v[60:63], v[104:107], v[96:99], v[60:63]
	s_nop 1
	ds_read_b128 v[32:35], v51 offset:36864
	ds_read_b128 v[96:99], v51 offset:38912
	ds_read_b128 v[108:111], v54 offset:49152
	s_waitcnt lgkmcnt(2)
	v_mfma_f32_16x16x32_bf16 v[72:75], v[92:95], v[32:35], v[72:75]
	v_mfma_f32_16x16x32_bf16 v[76:79], v[16:19], v[32:35], v[76:79]
	v_mfma_f32_16x16x32_bf16 v[80:83], v[0:3], v[32:35], v[80:83]
	v_mfma_f32_16x16x32_bf16 v[56:59], v[104:107], v[32:35], v[56:59]
	v_lshl_add_u64 v[32:33], v[40:41], 0, s[66:67]
	s_waitcnt lgkmcnt(1)
	v_mfma_f32_16x16x32_bf16 v[84:87], v[92:95], v[96:99], v[84:87]
	v_mfma_f32_16x16x32_bf16 v[92:95], v[16:19], v[96:99], v[36:39]
	v_mfma_f32_16x16x32_bf16 v[88:91], v[0:3], v[96:99], v[88:91]
	v_mfma_f32_16x16x32_bf16 v[0:3], v[104:107], v[96:99], v[4:7]
	ds_read_b128 v[16:19], v53 offset:32768
	ds_read_b128 v[96:99], v54 offset:51200
	ds_read_b128 v[36:39], v53 offset:34816
	ds_read_b128 v[104:107], v54 offset:53248
	global_load_lds_dwordx4 v[32:33], off
	ds_read_b128 v[32:35], v54 offset:55296
	s_mov_b32 m0, s55
	s_waitcnt lgkmcnt(0)
	v_mfma_f32_16x16x32_bf16 v[4:7], v[108:111], v[16:19], v[100:103]
	global_load_lds_dwordx4 v[42:43], off
	v_lshl_add_u64 v[42:43], v[40:41], 0, s[86:87]
	s_mov_b32 m0, s53
	s_mov_b64 s[86:87], 0x74500
	global_load_lds_dwordx4 v[42:43], off
	v_lshl_add_u64 v[42:43], v[40:41], 0, s[86:87]
	s_mov_b32 m0, s52
	v_mfma_f32_16x16x32_bf16 v[8:11], v[96:99], v[16:19], v[8:11]
	global_load_lds_dwordx4 v[42:43], off
	v_lshl_add_u64 v[42:43], v[44:45], 0, s[66:67]
	v_mfma_f32_16x16x32_bf16 v[12:15], v[104:107], v[16:19], v[12:15]
	s_mov_b32 m0, s43
	s_mov_b64 s[52:53], 0x4100
	global_load_lds_dwordx4 v[42:43], off
	v_mfma_f32_16x16x32_bf16 v[16:19], v[32:35], v[16:19], v[20:23]
	v_lshl_add_u64 v[42:43], v[44:45], 0, s[52:53]
	s_mov_b32 m0, s36
	s_mov_b64 s[52:53], 0x8100
	v_mfma_f32_16x16x32_bf16 v[20:23], v[108:111], v[36:39], v[24:27]
	global_load_lds_dwordx4 v[42:43], off
	v_lshl_add_u64 v[42:43], v[44:45], 0, s[52:53]
	v_mfma_f32_16x16x32_bf16 v[24:27], v[96:99], v[36:39], v[28:31]
	s_mov_b32 m0, s7
	s_mov_b64 s[52:53], 0xc100
	global_load_lds_dwordx4 v[42:43], off
	v_mfma_f32_16x16x32_bf16 v[28:31], v[104:107], v[36:39], v[68:71]
	v_lshl_add_u64 v[42:43], v[44:45], 0, s[52:53]
	s_mov_b32 m0, s5
	v_readlane_b32 s53, v255, 33
	ds_read_b128 v[68:71], v53 offset:36864
	v_mfma_f32_16x16x32_bf16 v[36:39], v[32:35], v[36:39], v[60:63]
	global_load_lds_dwordx4 v[42:43], off
	v_lshl_add_u64 v[42:43], v[40:41], 0, s[68:69]
	s_nop 0
	ds_read_b128 v[60:63], v53 offset:38912
	s_waitcnt lgkmcnt(0)
	v_mfma_f32_16x16x32_bf16 v[72:75], v[108:111], v[68:71], v[72:75]
	s_waitcnt vmcnt(0)
	s_waitcnt vmcnt(0)
	s_barrier
	v_mfma_f32_16x16x32_bf16 v[76:79], v[96:99], v[68:71], v[76:79]
	s_mov_b32 m0, s4
	s_mov_b64 s[4:5], 0x26d80
	v_mfma_f32_16x16x32_bf16 v[80:83], v[104:107], v[68:71], v[80:83]
	v_readlane_b32 s52, v255, 28
	v_mfma_f32_16x16x32_bf16 v[56:59], v[32:35], v[68:71], v[56:59]
	v_mfma_f32_16x16x32_bf16 v[68:71], v[108:111], v[60:63], v[84:87]
	v_mfma_f32_16x16x32_bf16 v[84:87], v[96:99], v[60:63], v[92:95]
	v_mfma_f32_16x16x32_bf16 v[88:91], v[104:107], v[60:63], v[88:91]
	s_nop 1
	ds_read_b128 v[92:95], v52 offset:16384
	v_mfma_f32_16x16x32_bf16 v[0:3], v[32:35], v[60:63], v[0:3]
	ds_read_b128 v[32:35], v52 offset:18432
	ds_read_b128 v[60:63], v51
	ds_read_b128 v[96:99], v51 offset:2048
	ds_read_b128 v[100:103], v52 offset:20480
	ds_read_b128 v[104:107], v52 offset:22528
	s_waitcnt lgkmcnt(3)
	v_mfma_f32_16x16x32_bf16 v[4:7], v[92:95], v[60:63], v[4:7]
	v_mfma_f32_16x16x32_bf16 v[8:11], v[32:35], v[60:63], v[8:11]
	s_waitcnt lgkmcnt(1)
	v_mfma_f32_16x16x32_bf16 v[12:15], v[100:103], v[60:63], v[12:15]
	s_waitcnt lgkmcnt(0)
	v_mfma_f32_16x16x32_bf16 v[16:19], v[104:107], v[60:63], v[16:19]
	v_mfma_f32_16x16x32_bf16 v[20:23], v[92:95], v[96:99], v[20:23]
	v_mfma_f32_16x16x32_bf16 v[24:27], v[32:35], v[96:99], v[24:27]
	v_mfma_f32_16x16x32_bf16 v[28:31], v[100:103], v[96:99], v[28:31]
	v_mfma_f32_16x16x32_bf16 v[36:39], v[104:107], v[96:99], v[36:39]
	ds_read_b128 v[60:63], v51 offset:4096
	ds_read_b128 v[96:99], v51 offset:6144
	s_waitcnt lgkmcnt(1)
	v_mfma_f32_16x16x32_bf16 v[72:75], v[92:95], v[60:63], v[72:75]
	v_mfma_f32_16x16x32_bf16 v[76:79], v[32:35], v[60:63], v[76:79]
	v_mfma_f32_16x16x32_bf16 v[80:83], v[100:103], v[60:63], v[80:83]
	v_mfma_f32_16x16x32_bf16 v[56:59], v[104:107], v[60:63], v[56:59]
	s_waitcnt lgkmcnt(0)
	v_mfma_f32_16x16x32_bf16 v[60:63], v[92:95], v[96:99], v[68:71]
	v_mfma_f32_16x16x32_bf16 v[68:71], v[32:35], v[96:99], v[84:87]
	ds_read_b128 v[32:35], v54 offset:16384
	v_mfma_f32_16x16x32_bf16 v[84:87], v[100:103], v[96:99], v[88:91]
	s_nop 2
	ds_read_b128 v[88:91], v53
	ds_read_b128 v[92:95], v54 offset:18432
	v_mfma_f32_16x16x32_bf16 v[0:3], v[104:107], v[96:99], v[0:3]
	ds_read_b128 v[96:99], v53 offset:2048
	ds_read_b128 v[100:103], v54 offset:20480
	ds_read_b128 v[104:107], v54 offset:22528
	global_load_lds_dwordx4 v[42:43], off
	v_lshl_add_u64 v[42:43], v[40:41], 0, s[4:5]
	s_mov_b32 m0, s41
	s_mov_b64 s[4:5], 0x4d980
	global_load_lds_dwordx4 v[42:43], off
	v_lshl_add_u64 v[42:43], v[40:41], 0, s[4:5]
	s_mov_b32 m0, s40
	s_mov_b64 s[4:5], 0x74580
	s_waitcnt lgkmcnt(0)
	v_mfma_f32_16x16x32_bf16 v[4:7], v[32:35], v[88:91], v[4:7]
	global_load_lds_dwordx4 v[42:43], off
	s_mov_b32 m0, s42
	v_mfma_f32_16x16x32_bf16 v[8:11], v[92:95], v[88:91], v[8:11]
	v_mfma_f32_16x16x32_bf16 v[12:15], v[100:103], v[88:91], v[12:15]
	v_mfma_f32_16x16x32_bf16 v[16:19], v[104:107], v[88:91], v[16:19]
	v_mfma_f32_16x16x32_bf16 v[88:91], v[92:95], v[96:99], v[24:27]
	s_nop 2
	v_lshl_add_u64 v[24:25], v[40:41], 0, s[4:5]
	global_load_lds_dwordx4 v[24:25], off
	ds_read_b128 v[24:27], v53 offset:4096
	v_mfma_f32_16x16x32_bf16 v[20:23], v[32:35], v[96:99], v[20:23]
	s_mov_b32 m0, s54
	s_mov_b64 s[4:5], 0x4180
	v_mfma_f32_16x16x32_bf16 v[108:111], v[100:103], v[96:99], v[28:31]
	s_nop 2
	v_lshl_add_u64 v[28:29], v[44:45], 0, s[68:69]
	v_mfma_f32_16x16x32_bf16 v[96:99], v[104:107], v[96:99], v[36:39]
	global_load_lds_dwordx4 v[28:29], off
	v_lshl_add_u64 v[28:29], v[44:45], 0, s[4:5]
	s_nop 0
	ds_read_b128 v[36:39], v53 offset:6144
	s_mov_b32 m0, s70
	s_mov_b64 s[4:5], 0x8180
	global_load_lds_dwordx4 v[28:29], off
	v_lshl_add_u64 v[28:29], v[44:45], 0, s[4:5]
	s_mov_b32 m0, s71
	s_mov_b64 s[4:5], 0xc180
	s_waitcnt lgkmcnt(0)
	v_mfma_f32_16x16x32_bf16 v[72:75], v[32:35], v[24:27], v[72:75]
	global_load_lds_dwordx4 v[28:29], off
	s_mov_b32 m0, s85
	v_mfma_f32_16x16x32_bf16 v[76:79], v[92:95], v[24:27], v[76:79]
	v_mfma_f32_16x16x32_bf16 v[80:83], v[100:103], v[24:27], v[80:83]
	v_mfma_f32_16x16x32_bf16 v[40:43], v[104:107], v[24:27], v[56:59]
	v_lshl_add_u64 v[24:25], v[44:45], 0, s[4:5]
	global_load_lds_dwordx4 v[24:25], off
	v_mfma_f32_16x16x32_bf16 v[24:27], v[100:103], v[36:39], v[84:87]
	s_waitcnt vmcnt(0)
	s_waitcnt vmcnt(0) lgkmcnt(0)
	s_barrier
	ds_read_b128 v[56:59], v52 offset:49152
	ds_read_b128 v[84:87], v52 offset:51200
	ds_read_b128 v[100:103], v52 offset:53248
	ds_read_b128 v[112:115], v52 offset:55296
	v_mfma_f32_16x16x32_bf16 v[32:35], v[32:35], v[36:39], v[60:63]
	ds_read_b128 v[120:123], v51 offset:34816
	v_and_b32_e32 v44, 0x80, v48
	v_mfma_f32_16x16x32_bf16 v[60:63], v[104:107], v[36:39], v[0:3]
	s_nop 2
	ds_read_b128 v[0:3], v51 offset:32768
	v_mfma_f32_16x16x32_bf16 v[28:31], v[92:95], v[36:39], v[68:71]
	s_waitcnt lgkmcnt(0)
	v_mfma_f32_16x16x32_bf16 v[68:71], v[56:59], v[0:3], v[4:7]
	v_mfma_f32_16x16x32_bf16 v[92:95], v[84:87], v[0:3], v[8:11]
	v_mfma_f32_16x16x32_bf16 v[104:107], v[100:103], v[0:3], v[12:15]
	v_mfma_f32_16x16x32_bf16 v[116:119], v[112:115], v[0:3], v[16:19]
	ds_read_b128 v[0:3], v54 offset:55296
	ds_read_b128 v[8:11], v54 offset:53248
	ds_read_b128 v[12:15], v54 offset:51200
	ds_read_b128 v[16:19], v54 offset:49152
	v_mfma_f32_16x16x32_bf16 v[124:127], v[56:59], v[120:123], v[20:23]
	ds_read_b128 v[4:7], v53 offset:38912
	s_nop 1
	ds_read_b128 v[20:23], v53 offset:36864
	ds_read_b128 v[36:39], v53 offset:34816
	ds_read_b128 v[52:55], v53 offset:32768
	ds_read_b128 v[128:131], v51 offset:38912
	ds_read_b128 v[132:135], v51 offset:36864
	v_or_b32_e32 v51, s6, v49
	v_lshl_or_b32 v44, v51, 1, v44
	v_ashrrev_i32_e32 v45, 31, v44
	v_lshl_add_u64 v[48:49], v[44:45], 2, s[10:11]
	s_waitcnt vmcnt(0)
	s_waitcnt lgkmcnt(0)
	s_barrier
	global_load_dword v64, v[48:49], off
	global_load_dword v66, v[48:49], off offset:128
	v_mfma_f32_16x16x32_bf16 v[88:91], v[84:87], v[120:123], v[88:91]
	v_mfma_f32_16x16x32_bf16 v[108:111], v[100:103], v[120:123], v[108:111]
	v_mfma_f32_16x16x32_bf16 v[96:99], v[112:115], v[120:123], v[96:99]
	v_mfma_f32_16x16x32_bf16 v[42:45], v[112:115], v[132:135], v[40:43]
	global_load_dword v120, v[48:49], off offset:256
	s_nop 1
	global_load_dword v40, v[48:49], off offset:384
	v_lshl_or_b32 v41, v47, 6, v51
	v_lshlrev_b32_e32 v47, 2, v50
	v_lshl_or_b32 v46, v46, 6, v47
	v_subrev_u32_e32 v46, s2, v46
	v_add_u32_e32 v50, s75, v46
	v_mfma_f32_16x16x32_bf16 v[46:49], v[16:19], v[52:55], v[68:71]
	v_ashrrev_i32_e32 v51, 31, v50
	v_mfma_f32_16x16x32_bf16 v[72:75], v[56:59], v[132:135], v[72:75]
	v_mfma_f32_16x16x32_bf16 v[32:35], v[56:59], v[128:131], v[32:35]
	s_waitcnt vmcnt(3)
	s_nop 3
	v_pk_mul_f32 v[46:47], v[46:47], v[64:65] op_sel_hi:[1,0]
	s_nop 0
	v_cvt_pk_bf16_f32 v58, v46, v47
	v_pk_mul_f32 v[46:47], v[48:49], v[64:65] op_sel_hi:[1,0]
	v_mfma_f32_16x16x32_bf16 v[76:79], v[84:87], v[132:135], v[76:79]
	v_cvt_pk_bf16_f32 v59, v46, v47
	v_mfma_f32_16x16x32_bf16 v[46:49], v[12:15], v[52:55], v[92:95]
	v_mfma_f32_16x16x32_bf16 v[28:31], v[84:87], v[128:131], v[28:31]
	v_lshlrev_b64 v[86:87], 1, v[50:51]
	s_nop 5
	v_pk_mul_f32 v[46:47], v[46:47], v[64:65] op_sel_hi:[1,0]
	v_mov_b64_e32 v[84:85], s[12:13]
	v_cvt_pk_bf16_f32 v50, v46, v47
	v_pk_mul_f32 v[46:47], v[48:49], v[64:65] op_sel_hi:[1,0]
	v_mad_i64_i32 v[56:57], s[4:5], v41, s78, v[84:85]
	v_cvt_pk_bf16_f32 v51, v46, v47
	v_mfma_f32_16x16x32_bf16 v[46:49], v[8:11], v[52:55], v[104:107]
	v_lshl_add_u64 v[68:69], v[56:57], 0, v[86:87]
	global_store_dwordx2 v[68:69], v[50:51], off offset:32
	global_store_dwordx2 v[68:69], v[58:59], off
	v_mfma_f32_16x16x32_bf16 v[50:53], v[0:3], v[52:55], v[116:119]
	v_mfma_f32_16x16x32_bf16 v[56:59], v[112:115], v[128:131], v[60:63]
	s_nop 2
	v_mul_f32_e64 v46, v46, v64
	v_mul_f32_e64 v47, v47, v64
	v_pk_mul_f32 v[48:49], v[48:49], v[64:65] op_sel_hi:[1,0]
	v_cvt_pk_bf16_f32 v46, v46, v47
	v_cvt_pk_bf16_f32 v47, v48, v49
	global_store_dwordx2 v[68:69], v[46:47], off offset:64
	v_mfma_f32_16x16x32_bf16 v[46:49], v[16:19], v[36:39], v[124:127]
	v_mul_f32_e64 v50, v50, v64
	v_mul_f32_e64 v51, v51, v64
	v_pk_mul_f32 v[60:61], v[52:53], v[64:65] op_sel_hi:[1,0]
	v_cvt_pk_bf16_f32 v54, v50, v51
	v_mfma_f32_16x16x32_bf16 v[50:53], v[12:15], v[36:39], v[88:91]
	v_cvt_pk_bf16_f32 v55, v60, v61
	global_store_dwordx2 v[68:69], v[54:55], off offset:96
	v_or_b32_e32 v54, 16, v41
	s_waitcnt vmcnt(6)
	v_pk_mul_f32 v[46:47], v[46:47], v[66:67] op_sel_hi:[1,0]
	v_mfma_f32_16x16x32_bf16 v[80:83], v[100:103], v[132:135], v[80:83]
	v_mad_i64_i32 v[54:55], s[4:5], v54, s78, v[84:85]
	v_cvt_pk_bf16_f32 v68, v46, v47
	v_pk_mul_f32 v[46:47], v[48:49], v[66:67] op_sel_hi:[1,0]
	v_mfma_f32_16x16x32_bf16 v[24:27], v[100:103], v[128:131], v[24:27]
	v_cvt_pk_bf16_f32 v69, v46, v47
	v_lshl_add_u64 v[54:55], v[54:55], 0, v[86:87]
	global_store_dwordx2 v[54:55], v[68:69], off
	v_mfma_f32_16x16x32_bf16 v[46:49], v[16:19], v[20:23], v[72:75]
	v_mul_f32_e64 v50, v50, v66
	v_mul_f32_e64 v51, v51, v66
	v_mfma_f32_16x16x32_bf16 v[68:71], v[12:15], v[20:23], v[76:79]
	v_cvt_pk_bf16_f32 v72, v50, v51
	v_pk_mul_f32 v[50:51], v[52:53], v[66:67] op_sel_hi:[1,0]
	s_nop 0
	v_cvt_pk_bf16_f32 v73, v50, v51
	v_mfma_f32_16x16x32_bf16 v[50:53], v[8:11], v[20:23], v[80:83]
	global_store_dwordx2 v[54:55], v[72:73], off offset:32
	v_mfma_f32_16x16x32_bf16 v[12:15], v[12:15], v[4:7], v[28:31]
	s_nop 2
	v_or_b32_e32 v28, 32, v41
	v_mfma_f32_16x16x32_bf16 v[60:63], v[8:11], v[36:39], v[108:111]
	v_mfma_f32_16x16x32_bf16 v[36:39], v[0:3], v[36:39], v[96:99]
	v_mfma_f32_16x16x32_bf16 v[20:23], v[0:3], v[20:23], v[42:45]
	s_nop 5
	v_mul_f32_e64 v60, v60, v66
	v_mul_f32_e64 v61, v61, v66
	v_cvt_pk_bf16_f32 v60, v60, v61
	v_mfma_f32_16x16x32_bf16 v[16:19], v[16:19], v[4:7], v[32:35]
	v_mul_f32_e64 v42, v62, v66
	v_mul_f32_e64 v43, v63, v66
	v_cvt_pk_bf16_f32 v61, v42, v43
	v_mfma_f32_16x16x32_bf16 v[8:11], v[8:11], v[4:7], v[24:27]
	v_mul_f32_e64 v32, v36, v66
	v_mul_f32_e64 v33, v37, v66
	v_pk_mul_f32 v[34:35], v[38:39], v[66:67] op_sel_hi:[1,0]
	v_cvt_pk_bf16_f32 v32, v32, v33
	v_mad_i64_i32 v[24:25], s[4:5], v28, s78, v[84:85]
	s_waitcnt vmcnt(7)
	v_pk_mul_f32 v[26:27], v[46:47], v[120:121] op_sel_hi:[1,0]
	v_mfma_f32_16x16x32_bf16 v[0:3], v[0:3], v[4:7], v[56:59]
	v_mul_f32_e64 v4, v48, v120
	v_mul_f32_e64 v5, v49, v120
	v_cvt_pk_bf16_f32 v26, v26, v27
	v_cvt_pk_bf16_f32 v27, v4, v5
	v_lshl_add_u64 v[4:5], v[24:25], 0, v[86:87]
	v_pk_mul_f32 v[6:7], v[68:69], v[120:121] op_sel_hi:[1,0]
	v_pk_mul_f32 v[24:25], v[70:71], v[120:121] op_sel_hi:[1,0]
	v_cvt_pk_bf16_f32 v6, v6, v7
	v_cvt_pk_bf16_f32 v7, v24, v25
	global_store_dwordx2 v[4:5], v[6:7], off offset:32
	v_pk_mul_f32 v[6:7], v[50:51], v[120:121] op_sel_hi:[1,0]
	v_pk_mul_f32 v[24:25], v[52:53], v[120:121] op_sel_hi:[1,0]
	v_cvt_pk_bf16_f32 v6, v6, v7
	v_cvt_pk_bf16_f32 v7, v24, v25
	global_store_dwordx2 v[4:5], v[6:7], off offset:64
	v_pk_mul_f32 v[6:7], v[20:21], v[120:121] op_sel_hi:[1,0]
	v_pk_mul_f32 v[20:21], v[22:23], v[120:121] op_sel_hi:[1,0]
	v_cvt_pk_bf16_f32 v6, v6, v7
	v_cvt_pk_bf16_f32 v7, v20, v21
	global_store_dwordx2 v[4:5], v[26:27], off
	global_store_dwordx2 v[4:5], v[6:7], off offset:96
	v_or_b32_e32 v4, 48, v41
	v_mad_i64_i32 v[4:5], s[4:5], v4, s78, v[84:85]
	s_waitcnt vmcnt(10)
	v_pk_mul_f32 v[6:7], v[16:17], v[40:41] op_sel_hi:[1,0]
	v_pk_mul_f32 v[16:17], v[18:19], v[40:41] op_sel_hi:[1,0]
	v_cvt_pk_bf16_f32 v6, v6, v7
	v_cvt_pk_bf16_f32 v7, v16, v17
	v_lshl_add_u64 v[4:5], v[4:5], 0, v[86:87]
	global_store_dwordx2 v[4:5], v[6:7], off
	v_pk_mul_f32 v[6:7], v[12:13], v[40:41] op_sel_hi:[1,0]
	v_pk_mul_f32 v[12:13], v[14:15], v[40:41] op_sel_hi:[1,0]
	v_cvt_pk_bf16_f32 v6, v6, v7
	v_cvt_pk_bf16_f32 v7, v12, v13
	global_store_dwordx2 v[4:5], v[6:7], off offset:32
	v_pk_mul_f32 v[6:7], v[8:9], v[40:41] op_sel_hi:[1,0]
	v_pk_mul_f32 v[8:9], v[10:11], v[40:41] op_sel_hi:[1,0]
	v_pk_mul_f32 v[0:1], v[0:1], v[40:41] op_sel_hi:[1,0]
	v_pk_mul_f32 v[2:3], v[2:3], v[40:41] op_sel_hi:[1,0]
	v_cvt_pk_bf16_f32 v33, v34, v35
	v_cvt_pk_bf16_f32 v6, v6, v7
	v_cvt_pk_bf16_f32 v7, v8, v9
	v_cvt_pk_bf16_f32 v0, v0, v1
	v_cvt_pk_bf16_f32 v1, v2, v3
	global_store_dwordx2 v[54:55], v[60:61], off offset:64
	global_store_dwordx2 v[54:55], v[32:33], off offset:96
	global_store_dwordx2 v[4:5], v[6:7], off offset:64
	global_store_dwordx2 v[4:5], v[0:1], off offset:96
	s_branch .LBB0_1988
